# DIFF attention: far-tile iterations run a hand-scheduled 2-tile body (MFMAs woven into softmax VALU, in-place exp/cvt, init block as MFMA SrcC)
# speedup vs baseline: 1.0582x; 1.0074x over previous
; #define LAS __attribute__((address_space(3)))
; template <int MODE>
; __device__ __forceinline__ void attn_item(const Params& P, int layer, int b, int h, int map, int qb) {
;     ...
;   auto qk = [&](f32x16& s0, f32x16& s1, float& boff, int bufi, int t) {
;     const ldsp_t kbuf = lds + bufi * KBUF;
;     __builtin_amdgcn_s_setprio(1);
;     boff = sa.m > -1e29f ? sa.m : 0.f;
;     const float init = ((MODE == 1 && !lookf(t)) ? cfar : 0.f) - boff;
; #pragma unroll
;     for (int q = 0; q < 16; ++q) { s0[q] = init; s1[q] = init; }
; #pragma unroll
;     for (int s = 0; s < NST; ++s) {
;       const bf16x8 a0 = *(LAS const bf16x8*)(kbuf + pr * KSTR + s * 32 + hh * 16);
;       const bf16x8 a1 = *(LAS const bf16x8*)(kbuf + (32 + pr) * KSTR + s * 32 + hh * 16);
;       s0 = __builtin_amdgcn_mfma_f32_32x32x16_bf16(a0, qf[s], s0, 0, 0, 0);
;       s1 = __builtin_amdgcn_mfma_f32_32x32x16_bf16(a1, qf[s], s1, 0, 0, 0);
;     }
;     __builtin_amdgcn_sched_group_barrier(0x100, 4, 0);
; #pragma unroll
;     for (int s = 0; s < NST - 2; ++s) { __builtin_amdgcn_sched_group_barrier(0x8, 2, 0); __builtin_amdgcn_sched_group_barrier(0x100, 2, 0); }
;     __builtin_amdgcn_sched_group_barrier(0x8, 4, 0);
;     __builtin_amdgcn_s_setprio(0);
;   };
;     ...
;   for (int i = 0; i < ntp; i += 2) {
;     const int base = (i & 2);
;     ATT_STEP(i, stY, base)
;     ATT_STEP(i + 1, stX, base + 1)
;     __syncthreads();
;   }
.LBB0_1251:
	s_and_b32 s78, s48, 2
	s_cmp_lt_u32 s48, 2
	s_cbranch_scc1 .Ldf_gen
	s_lshl_b32 s2, s48, 6
	s_sub_i32 s2, s80, s2
	s_cmpk_gt_i32 s2, 0xbf
	s_cbranch_scc1 .Ldf_fast
.Ldf_gen:
	s_cmp_ge_u32 s48, s62
	s_cbranch_scc1 .LBB0_1268
	s_lshl_b32 s84, s48, 6
	s_cmp_gt_i32 s84, s37
	s_cselect_b64 s[2:3], -1, 0
	s_or_b64 s[2:3], s[2:3], s[40:41]
	s_cmp_eq_u32 s48, 0
	v_cndmask_b32_e64 v34, 0, 1, s[2:3]
	v_cndmask_b32_e64 v35, 0, 1, s[40:41]
	s_cselect_b64 s[2:3], -1, 0
	v_cndmask_b32_e64 v34, v34, v35, s[2:3]
	v_and_b32_e32 v34, 1, v34
	v_cmp_eq_u32_e32 vcc, 1, v34
	s_cbranch_vccnz .LBB0_1268
	s_sub_i32 s6, s80, s84
	s_cmpk_gt_i32 s6, 0x7f
	s_cselect_b64 s[4:5], -1, 0
	s_cmpk_lt_i32 s6, 0x80
	s_cselect_b64 s[42:43], -1, 0
	s_mul_i32 s6, s78, 0x2400
	s_add_i32 s90, s6, 0
	s_or_b64 s[6:7], s[2:3], s[42:43]
	s_or_b32 s42, s84, 63
	s_cmp_gt_i32 s42, s36
	s_cselect_b64 s[42:43], -1, 0
	s_or_b64 s[42:43], s[2:3], s[42:43]
	s_setprio 1
	v_cndmask_b32_e64 v34, v221, 0, s[6:7]
	s_mul_i32 s6, s78, 0x1400
	v_add_u32_e32 v78, s6, v227
	ds_read_b128 v[66:69], v78 offset:2560
	ds_read_b128 v[70:73], v78
	v_cmp_lt_f32_e32 vcc, s87, v177
	ds_read_b128 v[74:77], v78 offset:32
	s_nop 0
	v_cndmask_b32_e32 v176, 0, v177, vcc
	v_sub_f32_e32 v34, v34, v176
	v_mov_b32_e32 v35, v34
	v_mov_b32_e32 v36, v34
	v_mov_b32_e32 v37, v34
	v_mov_b32_e32 v38, v34
	v_mov_b32_e32 v39, v34
	v_mov_b32_e32 v40, v34
	v_mov_b32_e32 v41, v34
	v_mov_b32_e32 v42, v34
	v_mov_b32_e32 v43, v34
	v_mov_b32_e32 v44, v34
	v_mov_b32_e32 v45, v34
	v_mov_b32_e32 v46, v34
	v_mov_b32_e32 v47, v34
	v_mov_b32_e32 v48, v34
	v_mov_b32_e32 v49, v34
	s_waitcnt lgkmcnt(1)
	s_nop 0
	v_mfma_f32_32x32x16_bf16 v[50:65], v[70:73], v[102:105], v[34:49]
	v_mfma_f32_32x32x16_bf16 v[34:49], v[66:69], v[102:105], v[34:49]
	ds_read_b128 v[66:69], v78 offset:2592
	s_waitcnt lgkmcnt(1)
	v_mfma_f32_32x32x16_bf16 v[50:65], v[74:77], v[98:101], v[50:65]
	s_waitcnt lgkmcnt(0)
	v_mfma_f32_32x32x16_bf16 v[34:49], v[66:69], v[98:101], v[34:49]
	s_setprio 0
	s_andn2_b64 vcc, exec, s[42:43]
	s_mov_b64 s[42:43], -1
	s_cbranch_vccz .LBB0_1263
	s_and_b64 vcc, exec, s[4:5]
	s_cbranch_vccz .LBB0_1259
	v_add3_u32 v66, s90, v224, v0
	ds_read_b128 v[146:149], v66 offset:20480
	ds_read_b128 v[142:145], v66 offset:20512
	ds_read_b128 v[150:153], v66 offset:25088
	ds_read_b128 v[138:141], v66 offset:25120
	ds_read_b128 v[134:137], v66 offset:20544
	ds_read_b128 v[126:129], v66 offset:20576
	ds_read_b128 v[130:133], v66 offset:25152
	ds_read_b128 v[122:125], v66 offset:25184
	v_max_f32_e32 v66, v51, v51
	v_max_f32_e32 v67, v50, v50
	v_max_f32_e32 v66, v67, v66
	v_max3_f32 v66, v66, v52, v53
	v_max3_f32 v66, v66, v54, v55
	v_max3_f32 v66, v66, v56, v57
	v_max3_f32 v66, v66, v58, v59
	v_max3_f32 v66, v66, v60, v61
	v_max3_f32 v66, v66, v62, v63
	v_max3_f32 v66, v66, v64, v65
	v_max3_f32 v66, v66, v34, v35
	v_max3_f32 v66, v66, v36, v37
	v_max3_f32 v66, v66, v38, v39
	v_max3_f32 v66, v66, v40, v41
	v_max3_f32 v66, v66, v42, v43
	v_max3_f32 v66, v66, v44, v45
	v_max3_f32 v66, v66, v46, v47
	v_exp_f32_e32 v204, v50
	v_exp_f32_e32 v180, v34
	v_exp_f32_e32 v205, v51
	v_exp_f32_e32 v181, v35
	v_exp_f32_e32 v206, v52
	v_exp_f32_e32 v188, v36
	v_exp_f32_e32 v207, v53
	v_exp_f32_e32 v189, v37
	v_exp_f32_e32 v208, v54
	v_exp_f32_e32 v194, v38
	v_exp_f32_e32 v209, v55
	v_exp_f32_e32 v195, v39
	v_exp_f32_e32 v192, v56
	v_exp_f32_e32 v196, v40
	v_exp_f32_e32 v193, v57
	v_exp_f32_e32 v197, v41
	v_exp_f32_e32 v198, v58
	v_exp_f32_e32 v178, v42
	v_exp_f32_e32 v199, v59
	v_exp_f32_e32 v179, v43
	v_exp_f32_e32 v202, v60
	v_exp_f32_e32 v182, v44
	v_exp_f32_e32 v203, v61
	v_exp_f32_e32 v183, v45
	v_exp_f32_e32 v200, v62
	v_exp_f32_e32 v190, v46
	v_exp_f32_e32 v201, v63
	v_exp_f32_e32 v191, v47
	v_exp_f32_e32 v184, v64
	v_exp_f32_e32 v186, v48
	v_exp_f32_e32 v185, v65
	v_exp_f32_e32 v187, v49
	v_max3_f32 v156, v66, v48, v49
	v_pk_add_f32 v[66:67], v[176:177], v[156:157]
	v_cmp_neq_f32_e64 s[4:5], v177, v176
	v_cmp_gt_f32_e32 vcc, v66, v67
	s_or_b64 vcc, s[4:5], vcc
	s_cbranch_vccz .LBB0_1257
	v_mov_b32_e32 v66, v210
	v_max_f32_e32 v68, v156, v156
	v_lshlrev_b32_e32 v66, 2, v66
	v_xor_b32_e32 v66, 0x80, v66
	ds_bpermute_b32 v66, v66, v156
	s_waitcnt lgkmcnt(0)
	v_max_f32_e32 v66, v66, v66
	v_max_f32_e32 v66, v68, v66
	v_add_f32_e32 v66, v176, v66
	v_cmp_gt_f32_e32 vcc, v66, v67
	s_nop 1
	v_cndmask_b32_e32 v156, v177, v66, vcc
	v_sub_f32_e32 v66, v176, v156
	v_min_f32_e32 v66, 0x42f00000, v66
	v_sub_f32_e32 v67, v177, v156
	v_exp_f32_e32 v66, v66
	v_exp_f32_e32 v158, v67
	v_pk_mul_f32 v[184:185], v[184:185], v[66:67] op_sel_hi:[1,0]
	v_pk_mul_f32 v[200:201], v[200:201], v[66:67] op_sel_hi:[1,0]
	v_pk_mul_f32 v[202:203], v[202:203], v[66:67] op_sel_hi:[1,0]
	v_pk_mul_f32 v[198:199], v[198:199], v[66:67] op_sel_hi:[1,0]
	v_pk_mul_f32 v[192:193], v[192:193], v[66:67] op_sel_hi:[1,0]
	v_pk_mul_f32 v[208:209], v[208:209], v[66:67] op_sel_hi:[1,0]
	v_pk_mul_f32 v[206:207], v[206:207], v[66:67] op_sel_hi:[1,0]
	v_pk_mul_f32 v[204:205], v[204:205], v[66:67] op_sel_hi:[1,0]
	v_pk_mul_f32 v[186:187], v[186:187], v[66:67] op_sel_hi:[1,0]
	v_pk_mul_f32 v[190:191], v[190:191], v[66:67] op_sel_hi:[1,0]
	v_pk_mul_f32 v[182:183], v[182:183], v[66:67] op_sel_hi:[1,0]
	v_pk_mul_f32 v[178:179], v[178:179], v[66:67] op_sel_hi:[1,0]
	v_pk_mul_f32 v[196:197], v[196:197], v[66:67] op_sel_hi:[1,0]
	v_pk_mul_f32 v[194:195], v[194:195], v[66:67] op_sel_hi:[1,0]
	v_pk_mul_f32 v[188:189], v[188:189], v[66:67] op_sel_hi:[1,0]
	v_pk_mul_f32 v[180:181], v[180:181], v[66:67] op_sel_hi:[1,0]
	v_pk_mul_f32 v[32:33], v[32:33], v[158:159] op_sel_hi:[1,0]
	v_pk_mul_f32 v[30:31], v[30:31], v[158:159] op_sel_hi:[1,0]
	v_pk_mul_f32 v[28:29], v[28:29], v[158:159] op_sel_hi:[1,0]
	v_pk_mul_f32 v[26:27], v[26:27], v[158:159] op_sel_hi:[1,0]
	v_pk_mul_f32 v[24:25], v[24:25], v[158:159] op_sel_hi:[1,0]
	v_pk_mul_f32 v[22:23], v[22:23], v[158:159] op_sel_hi:[1,0]
	v_pk_mul_f32 v[20:21], v[20:21], v[158:159] op_sel_hi:[1,0]
	v_pk_mul_f32 v[18:19], v[18:19], v[158:159] op_sel_hi:[1,0]
	v_pk_mul_f32 v[16:17], v[16:17], v[158:159] op_sel_hi:[1,0]
	v_pk_mul_f32 v[14:15], v[14:15], v[158:159] op_sel_hi:[1,0]
	v_pk_mul_f32 v[12:13], v[12:13], v[158:159] op_sel_hi:[1,0]
	v_pk_mul_f32 v[10:11], v[10:11], v[158:159] op_sel_hi:[1,0]
	v_pk_mul_f32 v[8:9], v[8:9], v[158:159] op_sel_hi:[1,0]
	v_pk_mul_f32 v[6:7], v[6:7], v[158:159] op_sel_hi:[1,0]
	v_pk_mul_f32 v[4:5], v[4:5], v[158:159] op_sel_hi:[1,0]
	v_pk_mul_f32 v[2:3], v[2:3], v[158:159] op_sel_hi:[1,0]
	v_mul_f32_e32 v229, v228, v158
	s_branch .LBB0_1258

; #define LAS __attribute__((address_space(3)))
; __device__ __forceinline__ void softmax_tile(f32x16& s0, f32x16& s1, SM& st, float boff, ldsp_t vb, int hh, int r) {
;     ...
;   float zmax = max3f(s0[0], s0[1], s0[2]);
; #pragma unroll
;   for (int k = 0; k < 6; ++k) zmax = max3f(zmax, s0[3 + 2 * k], s0[4 + 2 * k]);
;   zmax = max3f(zmax, s0[15], s1[0]);
; #pragma unroll
;   for (int k = 0; k < 7; ++k) zmax = max3f(zmax, s1[1 + 2 * k], s1[2 + 2 * k]);
;   zmax = fmaxf(zmax, s1[15]);
; #pragma unroll
;   for (int i = 0; i < 16; ++i) { s0[i] = __builtin_amdgcn_exp2f(s0[i]); s1[i] = __builtin_amdgcn_exp2f(s1[i]); }
;   if (__any((zmax + boff > st.m + DEFER_THR) || (st.m != boff))) {
;     const float zt = max32(zmax) + boff; const bool need = zt > st.m + DEFER_THR;
;     const float mn = need ? zt : st.m, alpha = __builtin_amdgcn_exp2f(st.m - mn), f = __builtin_amdgcn_exp2f(__builtin_fminf(boff - mn, 120.f)); st.m = mn;
; #pragma unroll
;     for (int i = 0; i < 16; ++i) { s0[i] *= f; s1[i] *= f; st.o0[i] *= alpha; st.o1[i] *= alpha; }
;     st.l *= alpha;
;   }
;   float ls = 0.f;
; #pragma unroll
;   for (int i = 0; i < 16; ++i) ls += s0[i] + s1[i];
; template <int MODE>
; __device__ __forceinline__ void attn_item(const Params& P, int layer, int b, int h, int map, int qb) {
;     ...
;   auto qk = [&](f32x16& s0, f32x16& s1, float& boff, int bufi, int t) {
;     const ldsp_t kbuf = lds + bufi * KBUF;
;     __builtin_amdgcn_s_setprio(1);
;     boff = sa.m > -1e29f ? sa.m : 0.f;
;     const float init = ((MODE == 1 && !lookf(t)) ? cfar : 0.f) - boff;
; #pragma unroll
;     for (int q = 0; q < 16; ++q) { s0[q] = init; s1[q] = init; }
; #pragma unroll
;     for (int s = 0; s < NST; ++s) {
;       const bf16x8 a0 = *(LAS const bf16x8*)(kbuf + pr * KSTR + s * 32 + hh * 16);
;       const bf16x8 a1 = *(LAS const bf16x8*)(kbuf + (32 + pr) * KSTR + s * 32 + hh * 16);
;       s0 = __builtin_amdgcn_mfma_f32_32x32x16_bf16(a0, qf[s], s0, 0, 0, 0);
;       s1 = __builtin_amdgcn_mfma_f32_32x32x16_bf16(a1, qf[s], s1, 0, 0, 0);
;     }
;     __builtin_amdgcn_sched_group_barrier(0x100, 4, 0);
; #pragma unroll
;     for (int s = 0; s < NST - 2; ++s) { __builtin_amdgcn_sched_group_barrier(0x8, 2, 0); __builtin_amdgcn_sched_group_barrier(0x100, 2, 0); }
;     __builtin_amdgcn_sched_group_barrier(0x8, 4, 0);
;     __builtin_amdgcn_s_setprio(0);
;   };
.Ldf_fast:
	s_mul_i32 s6, s78, 0x1400
	s_or_b32 s7, s78, 1
	s_mul_i32 s2, s7, 0x1400
	v_add_u32_e32 v160, s6, v227
	v_add_u32_e32 v161, s2, v227
	ds_read_b128 v[178:181], v160
	ds_read_b128 v[182:185], v160 offset:2560
	ds_read_b128 v[186:189], v160 offset:32
	ds_read_b128 v[190:193], v160 offset:2592
	ds_read_b128 v[194:197], v161
	ds_read_b128 v[198:201], v161 offset:2560
	ds_read_b128 v[202:205], v161 offset:32
	ds_read_b128 v[206:209], v161 offset:2592
	v_cmp_lt_f32_e32 vcc, s87, v177
	s_mul_i32 s6, s78, 0x2400
	s_mul_i32 s7, s7, 0x2400
	v_cndmask_b32_e32 v176, 0, v177, vcc
	v_sub_f32_e32 v230, v221, v176
	v_mov_b32_e32 v231, v230
	v_mov_b32_e32 v232, v230
	v_mov_b32_e32 v233, v230
	v_mov_b32_e32 v234, v230
	v_mov_b32_e32 v235, v230
	v_mov_b32_e32 v236, v230
	v_mov_b32_e32 v237, v230
	v_mov_b32_e32 v238, v230
	v_mov_b32_e32 v239, v230
	v_mov_b32_e32 v240, v230
	v_mov_b32_e32 v241, v230
	v_mov_b32_e32 v242, v230
	v_mov_b32_e32 v243, v230
	v_mov_b32_e32 v244, v230
	v_mov_b32_e32 v245, v230
	v_add3_u32 v158, s6, v224, v0
	v_add3_u32 v246, s7, v224, v0
	s_waitcnt lgkmcnt(7)
	v_mfma_f32_32x32x16_bf16 v[50:65], v[178:181], v[102:105], v[230:245]
	s_waitcnt lgkmcnt(6)
	v_mfma_f32_32x32x16_bf16 v[34:49], v[182:185], v[102:105], v[230:245]
	s_waitcnt lgkmcnt(5)
	v_mfma_f32_32x32x16_bf16 v[50:65], v[186:189], v[98:101], v[50:65]
	s_waitcnt lgkmcnt(4)
	v_mfma_f32_32x32x16_bf16 v[34:49], v[190:193], v[98:101], v[34:49]
	ds_read_b128 v[146:149], v158 offset:20480
	ds_read_b128 v[142:145], v158 offset:20512
	ds_read_b128 v[150:153], v158 offset:25088
	ds_read_b128 v[138:141], v158 offset:25120
	ds_read_b128 v[134:137], v158 offset:20544
	ds_read_b128 v[126:129], v158 offset:20576
	ds_read_b128 v[130:133], v158 offset:25152
	ds_read_b128 v[122:125], v158 offset:25184
	s_waitcnt lgkmcnt(11)
	v_mfma_f32_32x32x16_bf16 v[82:97], v[194:197], v[102:105], v[230:245]
	s_waitcnt lgkmcnt(10)
	v_mfma_f32_32x32x16_bf16 v[66:81], v[198:201], v[102:105], v[230:245]
	v_max3_f32 v156, v50, v51, v52
	v_max3_f32 v156, v156, v53, v54
	v_max3_f32 v156, v156, v55, v56
	v_max3_f32 v156, v156, v57, v58
	v_max3_f32 v156, v156, v59, v60
	v_max3_f32 v156, v156, v61, v62
	v_max3_f32 v156, v156, v63, v64
	v_max3_f32 v156, v156, v65, v34
	v_max3_f32 v156, v156, v35, v36
	v_max3_f32 v156, v156, v37, v38
	v_max3_f32 v156, v156, v39, v40
	v_max3_f32 v156, v156, v41, v42
	v_max3_f32 v156, v156, v43, v44
	v_max3_f32 v156, v156, v45, v46
	v_max3_f32 v156, v156, v47, v48
	v_max_f32_e32 v156, v156, v49
	v_exp_f32_e32 v50, v50
	v_exp_f32_e32 v34, v34
	s_waitcnt lgkmcnt(9)
	v_mfma_f32_32x32x16_bf16 v[82:97], v[202:205], v[98:101], v[82:97]
	v_exp_f32_e32 v51, v51
	v_exp_f32_e32 v35, v35
	v_exp_f32_e32 v52, v52
	v_exp_f32_e32 v36, v36
	v_exp_f32_e32 v53, v53
	v_exp_f32_e32 v37, v37
	v_exp_f32_e32 v54, v54
	v_exp_f32_e32 v38, v38
	v_exp_f32_e32 v55, v55
	v_exp_f32_e32 v39, v39
	v_exp_f32_e32 v56, v56
	v_exp_f32_e32 v40, v40
	v_exp_f32_e32 v57, v57
	v_exp_f32_e32 v41, v41
	v_exp_f32_e32 v58, v58
	v_exp_f32_e32 v42, v42
	v_exp_f32_e32 v59, v59
	v_exp_f32_e32 v43, v43
	v_exp_f32_e32 v60, v60
	v_exp_f32_e32 v44, v44
	s_waitcnt lgkmcnt(8)
	v_mfma_f32_32x32x16_bf16 v[66:81], v[206:209], v[98:101], v[66:81]
	v_exp_f32_e32 v61, v61
	v_exp_f32_e32 v45, v45
	v_exp_f32_e32 v62, v62
	v_exp_f32_e32 v46, v46
	v_exp_f32_e32 v63, v63
	v_exp_f32_e32 v47, v47
	v_exp_f32_e32 v64, v64
	v_exp_f32_e32 v48, v48
	v_exp_f32_e32 v65, v65
	v_exp_f32_e32 v49, v49
	v_pk_add_f32 v[160:161], v[176:177], v[156:157]
	v_cmp_neq_f32_e64 s[4:5], v177, v176
	v_cmp_gt_f32_e32 vcc, v160, v161
	s_or_b64 vcc, s[4:5], vcc
	s_cbranch_vccnz .Ldf_slow_a
.Ldf_back_a:
	v_add_f32_e32 v250, v50, v34
	v_add_f32_e32 v249, 0, v250
	v_add_f32_e32 v250, v51, v35
	v_add_f32_e32 v249, v250, v249
	v_add_f32_e32 v250, v52, v36
	v_add_f32_e32 v249, v250, v249
	v_add_f32_e32 v250, v53, v37
	v_add_f32_e32 v249, v250, v249
	v_add_f32_e32 v250, v54, v38
	v_add_f32_e32 v249, v250, v249
	v_add_f32_e32 v250, v55, v39
	v_add_f32_e32 v249, v250, v249
	v_add_f32_e32 v250, v56, v40
	v_add_f32_e32 v249, v250, v249
	v_add_f32_e32 v250, v57, v41
	v_add_f32_e32 v249, v250, v249
	v_cvt_pk_bf16_f32 v50, v50, v51
	v_cvt_pk_bf16_f32 v51, v52, v53
	v_cvt_pk_bf16_f32 v52, v54, v55
	v_cvt_pk_bf16_f32 v53, v56, v57
	v_add_f32_e32 v250, v58, v42
	v_add_f32_e32 v249, v250, v249
	s_waitcnt lgkmcnt(7)
	v_mfma_f32_32x32x16_bf16 v[18:33], v[146:149], v[50:53], v[18:33]
	v_add_f32_e32 v250, v59, v43
	v_add_f32_e32 v249, v250, v249
	v_add_f32_e32 v250, v60, v44
	s_waitcnt lgkmcnt(5)
	v_mfma_f32_32x32x16_bf16 v[2:17], v[150:153], v[50:53], v[2:17]
	v_add_f32_e32 v249, v250, v249
	v_add_f32_e32 v250, v61, v45
	v_add_f32_e32 v249, v250, v249
	v_add_f32_e32 v250, v62, v46
	v_add_f32_e32 v249, v250, v249
	v_add_f32_e32 v250, v63, v47
	v_add_f32_e32 v249, v250, v249
	v_add_f32_e32 v250, v64, v48
	ds_read_b128 v[178:181], v246 offset:20480
	ds_read_b128 v[182:185], v246 offset:20512
	ds_read_b128 v[186:189], v246 offset:25088
	ds_read_b128 v[190:193], v246 offset:25120
	ds_read_b128 v[194:197], v246 offset:20544
	ds_read_b128 v[198:201], v246 offset:20576
	ds_read_b128 v[202:205], v246 offset:25152
	ds_read_b128 v[206:209], v246 offset:25184
	v_add_f32_e32 v249, v250, v249
	v_add_f32_e32 v250, v65, v49
	v_add_f32_e32 v249, v250, v249
	v_cvt_pk_bf16_f32 v58, v58, v59
	v_cvt_pk_bf16_f32 v59, v60, v61
	v_cvt_pk_bf16_f32 v60, v62, v63
	v_cvt_pk_bf16_f32 v61, v64, v65
	v_cvt_pk_bf16_f32 v34, v34, v35
	v_cvt_pk_bf16_f32 v35, v36, v37
	s_waitcnt lgkmcnt(14)
; #define LAS __attribute__((address_space(3)))
; __device__ __forceinline__ unsigned cvt_pk_bf16(float lo, float hi) { const f32x2 v = {lo, hi}; return __builtin_bit_cast(unsigned, __builtin_convertvector(v, bf16v2)); }
; __device__ __forceinline__ void softmax_tile(f32x16& s0, f32x16& s1, SM& st, float boff, ldsp_t vb, int hh, int r) {
;     ...
;   float ls = 0.f;
; #pragma unroll
;   for (int i = 0; i < 16; ++i) ls += s0[i] + s1[i];
;   st.l += ls;
;   bf16x8 pf[2][2];
; #pragma unroll
;   for (int s2 = 0; s2 < 2; ++s2) {
;     u32x4 w0, w1;
;     w0.x = cvt_pk_bf16(s0[8 * s2 + 0], s0[8 * s2 + 1]); w0.y = cvt_pk_bf16(s0[8 * s2 + 2], s0[8 * s2 + 3]); w0.z = cvt_pk_bf16(s0[8 * s2 + 4], s0[8 * s2 + 5]); w0.w = cvt_pk_bf16(s0[8 * s2 + 6], s0[8 * s2 + 7]);
;     w1.x = cvt_pk_bf16(s1[8 * s2 + 0], s1[8 * s2 + 1]); w1.y = cvt_pk_bf16(s1[8 * s2 + 2], s1[8 * s2 + 3]); w1.z = cvt_pk_bf16(s1[8 * s2 + 4], s1[8 * s2 + 5]); w1.w = cvt_pk_bf16(s1[8 * s2 + 6], s1[8 * s2 + 7]);
;     pf[0][s2] = __builtin_bit_cast(bf16x8, w0); pf[1][s2] = __builtin_bit_cast(bf16x8, w1);
;   }
; #pragma unroll
;   for (int kb = 0; kb < 2; ++kb)
; #pragma unroll
;     for (int s2 = 0; s2 < 2; ++s2) {
;       st.o0 = __builtin_amdgcn_mfma_f32_32x32x16_bf16(va0[kb][s2], pf[kb][s2], st.o0, 0, 0, 0);
;       st.o1 = __builtin_amdgcn_mfma_f32_32x32x16_bf16(va1[kb][s2], pf[kb][s2], st.o1, 0, 0, 0);
;     }
; template <int MODE>
; __device__ __forceinline__ void attn_item(const Params& P, int layer, int b, int h, int map, int qb) {
;     ...
;   auto issue = [&](Stage& st, int t) {
; #pragma unroll
;     for (int u = 0; u < NLK; ++u) { int c = tid + 512 * u; if (c >= NKC) c -= (NKC % 512 == 0 ? 512 : NKC % 512);
;       const int row = c / CPR, cc = c % CPR; st.k[u] = *(const u32x4*)(kp + (size_t)(64 * t + row) * KLD + cc * 8); }
;     { const int row = tid >> 3, cc = tid & 7; st.v = *(const u32x4*)(vp + (size_t)row * E + 64 * t + cc * 8); }
;   };
;   auto commit = [&](const Stage& st, int bufi) {
; #pragma unroll
;     for (int u = 0; u < NLK; ++u) { int c = tid + 512 * u; if (c >= NKC) c -= (NKC % 512 == 0 ? 512 : NKC % 512);
;       const int row = c / CPR, cc = c % CPR; *(LAS u32x4*)(lds + bufi * KBUF + row * KSTR + cc * 16) = st.k[u]; }
;     { const int row = tid >> 3, cc = tid & 7; *(LAS u32x4*)(lds + 4 * KBUF + bufi * VBUF + row * 144 + cc * 16) = st.v; }
	v_mfma_f32_32x32x16_bf16 v[18:33], v[142:145], v[58:61], v[18:33]
	v_cvt_pk_bf16_f32 v36, v38, v39
	v_cvt_pk_bf16_f32 v37, v40, v41
	v_cvt_pk_bf16_f32 v42, v42, v43
	v_cvt_pk_bf16_f32 v43, v44, v45
	v_cvt_pk_bf16_f32 v44, v46, v47
	v_cvt_pk_bf16_f32 v45, v48, v49
	v_max3_f32 v247, v82, v83, v84
	v_max3_f32 v247, v247, v85, v86
	v_max3_f32 v247, v247, v87, v88
	v_max3_f32 v247, v247, v89, v90
	v_max3_f32 v247, v247, v91, v92
	v_max3_f32 v247, v247, v93, v94
	v_max3_f32 v247, v247, v95, v96
	v_max3_f32 v247, v247, v97, v66
	v_max3_f32 v247, v247, v67, v68
	s_waitcnt lgkmcnt(12)
	v_mfma_f32_32x32x16_bf16 v[2:17], v[138:141], v[58:61], v[2:17]
	v_max3_f32 v247, v247, v69, v70
	v_max3_f32 v247, v247, v71, v72
	v_max3_f32 v247, v247, v73, v74
	v_max3_f32 v247, v247, v75, v76
	v_max3_f32 v247, v247, v77, v78
	v_max3_f32 v247, v247, v79, v80
	v_max_f32_e32 v247, v247, v81
	v_exp_f32_e32 v82, v82
	v_exp_f32_e32 v66, v66
	v_exp_f32_e32 v83, v83
	v_exp_f32_e32 v67, v67
	v_exp_f32_e32 v84, v84
	s_waitcnt lgkmcnt(11)
	v_mfma_f32_32x32x16_bf16 v[18:33], v[134:137], v[34:37], v[18:33]
	v_exp_f32_e32 v68, v68
	v_exp_f32_e32 v85, v85
	v_exp_f32_e32 v69, v69
	v_exp_f32_e32 v86, v86
	v_exp_f32_e32 v70, v70
	v_exp_f32_e32 v87, v87
	v_exp_f32_e32 v71, v71
	v_exp_f32_e32 v88, v88
	s_waitcnt lgkmcnt(9)
	v_mfma_f32_32x32x16_bf16 v[2:17], v[130:133], v[34:37], v[2:17]
	v_exp_f32_e32 v72, v72
	v_exp_f32_e32 v89, v89
	v_exp_f32_e32 v73, v73
	v_exp_f32_e32 v90, v90
	v_exp_f32_e32 v74, v74
	v_exp_f32_e32 v91, v91
	v_exp_f32_e32 v75, v75
	v_exp_f32_e32 v92, v92
	s_waitcnt lgkmcnt(10)
	v_mfma_f32_32x32x16_bf16 v[18:33], v[126:129], v[42:45], v[18:33]
	v_exp_f32_e32 v76, v76
	v_exp_f32_e32 v93, v93
	v_exp_f32_e32 v77, v77
	v_exp_f32_e32 v94, v94
	v_exp_f32_e32 v78, v78
	v_exp_f32_e32 v95, v95
	v_exp_f32_e32 v79, v79
	v_exp_f32_e32 v96, v96
	s_waitcnt lgkmcnt(8)
	v_mfma_f32_32x32x16_bf16 v[2:17], v[122:125], v[42:45], v[2:17]
	v_exp_f32_e32 v80, v80
	v_exp_f32_e32 v97, v97
	v_exp_f32_e32 v81, v81
	v_add_f32_e32 v228, v228, v249
	v_add_f32_e32 v160, v176, v247
	v_add_f32_e32 v161, v177, v157
	v_cmp_neq_f32_e64 s[4:5], v177, v176
	v_cmp_gt_f32_e32 vcc, v160, v161
	s_or_b64 vcc, s[4:5], vcc
	s_cbranch_vccnz .Ldf_slow_b
.Ldf_back_b:
	v_add_f32_e32 v250, v82, v66
	v_add_f32_e32 v249, 0, v250
	v_add_f32_e32 v250, v83, v67
	v_add_f32_e32 v249, v250, v249
	v_add_f32_e32 v250, v84, v68
	v_add_f32_e32 v249, v250, v249
	v_add_f32_e32 v250, v85, v69
	v_add_f32_e32 v249, v250, v249
	v_add_f32_e32 v250, v86, v70
	v_add_f32_e32 v249, v250, v249
	v_add_f32_e32 v250, v87, v71
	v_add_f32_e32 v249, v250, v249
	v_add_f32_e32 v250, v88, v72
	v_add_f32_e32 v249, v250, v249
	v_add_f32_e32 v250, v89, v73
	v_add_f32_e32 v249, v250, v249
	v_cvt_pk_bf16_f32 v82, v82, v83
	v_cvt_pk_bf16_f32 v83, v84, v85
	v_cvt_pk_bf16_f32 v84, v86, v87
	v_cvt_pk_bf16_f32 v85, v88, v89
	v_add_f32_e32 v250, v90, v74
	v_add_f32_e32 v249, v250, v249
	s_waitcnt lgkmcnt(7)
	v_mfma_f32_32x32x16_bf16 v[18:33], v[178:181], v[82:85], v[18:33]
	s_waitcnt lgkmcnt(5)
	v_mfma_f32_32x32x16_bf16 v[2:17], v[186:189], v[82:85], v[2:17]
	v_add_f32_e32 v250, v91, v75
	v_add_f32_e32 v249, v250, v249
	v_add_f32_e32 v250, v92, v76
	v_add_f32_e32 v249, v250, v249
	v_add_f32_e32 v250, v93, v77
	v_add_f32_e32 v249, v250, v249
	v_add_f32_e32 v250, v94, v78
	v_add_f32_e32 v249, v250, v249
	v_add_f32_e32 v250, v95, v79
	v_add_f32_e32 v249, v250, v249
	v_add_f32_e32 v250, v96, v80
	v_add_f32_e32 v249, v250, v249
	v_add_f32_e32 v250, v97, v81
	v_add_f32_e32 v249, v250, v249
	v_cvt_pk_bf16_f32 v90, v90, v91
	v_cvt_pk_bf16_f32 v91, v92, v93
	v_cvt_pk_bf16_f32 v92, v94, v95
	v_cvt_pk_bf16_f32 v93, v96, v97
	v_cvt_pk_bf16_f32 v66, v66, v67
	v_cvt_pk_bf16_f32 v67, v68, v69
	s_waitcnt lgkmcnt(6)
	v_mfma_f32_32x32x16_bf16 v[18:33], v[182:185], v[90:93], v[18:33]
	s_waitcnt lgkmcnt(4)
	v_mfma_f32_32x32x16_bf16 v[2:17], v[190:193], v[90:93], v[2:17]
	v_cvt_pk_bf16_f32 v68, v70, v71
	v_cvt_pk_bf16_f32 v69, v72, v73
	v_cvt_pk_bf16_f32 v74, v74, v75
	v_cvt_pk_bf16_f32 v75, v76, v77
	s_waitcnt lgkmcnt(3)
	v_mfma_f32_32x32x16_bf16 v[18:33], v[194:197], v[66:69], v[18:33]
	s_waitcnt lgkmcnt(1)
	v_mfma_f32_32x32x16_bf16 v[2:17], v[202:205], v[66:69], v[2:17]
	v_cvt_pk_bf16_f32 v76, v78, v79
	v_cvt_pk_bf16_f32 v77, v80, v81
	v_add_f32_e32 v228, v228, v249
	s_waitcnt lgkmcnt(2)
	v_mfma_f32_32x32x16_bf16 v[18:33], v[198:201], v[74:77], v[18:33]
	s_waitcnt lgkmcnt(0)
	v_mfma_f32_32x32x16_bf16 v[2:17], v[206:209], v[74:77], v[2:17]
	s_xor_b32 s2, s78, 2
	s_mul_i32 s3, s2, 0x1400
	v_add_u32_e32 v160, s3, v171
	s_mulk_i32 s2, 0x2400
	s_waitcnt vmcnt(3)
	ds_write_b128 v160, v[106:109]
	v_add_u32_e32 v160, s2, v222
	s_add_i32 s2, s48, 4
	s_min_i32 s2, s2, s63
	s_lshl_b32 s90, s2, 6
	s_waitcnt vmcnt(2)
	ds_write_b128 v160, v[110:113] offset:20480
	v_add_u32_e32 v160, s90, v170
	v_ashrrev_i32_e32 v161, 31, v160
	v_lshlrev_b64 v[160:161], 7, v[160:161]
	v_lshl_add_u64 v[160:161], v[174:175], 0, v[160:161]
	v_lshl_add_u64 v[250:251], s[90:91], 1, v[172:173]
	global_load_dwordx4 v[106:109], v[160:161], off
	global_load_dwordx4 v[110:113], v[250:251], off
	s_xor_b32 s2, s78, 3
	s_mul_i32 s3, s2, 0x1400
	v_add_u32_e32 v160, s3, v171
	s_mulk_i32 s2, 0x2400
	s_waitcnt vmcnt(3)
	ds_write_b128 v160, v[114:117]
	v_add_u32_e32 v160, s2, v222
	s_add_i32 s2, s48, 5
	s_min_i32 s2, s2, s63
	s_lshl_b32 s90, s2, 6
	s_waitcnt vmcnt(2)
	ds_write_b128 v160, v[118:121] offset:20480
	v_add_u32_e32 v160, s90, v170
	v_ashrrev_i32_e32 v161, 31, v160
	v_lshlrev_b64 v[160:161], 7, v[160:161]
	v_lshl_add_u64 v[160:161], v[174:175], 0, v[160:161]
	v_lshl_add_u64 v[250:251], s[90:91], 1, v[172:173]
	global_load_dwordx4 v[114:117], v[160:161], off
	global_load_dwordx4 v[118:121], v[250:251], off
	s_add_i32 s48, s48, 2
	s_cmp_gt_u32 s48, s62
	s_waitcnt lgkmcnt(0)
	s_barrier
	s_cbranch_scc1 .LBB0_1288
	s_branch .LBB0_1251
; __device__ __forceinline__ float max32(float v) { return __builtin_fmaxf(v, xhalf(v)); }
; __device__ __forceinline__ void softmax_tile(f32x16& s0, f32x16& s1, SM& st, float boff, ldsp_t vb, int hh, int r) {
;     ...
;   if (__any((zmax + boff > st.m + DEFER_THR) || (st.m != boff))) {
;     const float zt = max32(zmax) + boff; const bool need = zt > st.m + DEFER_THR;
;     const float mn = need ? zt : st.m, alpha = __builtin_amdgcn_exp2f(st.m - mn), f = __builtin_amdgcn_exp2f(__builtin_fminf(boff - mn, 120.f)); st.m = mn;
; #pragma unroll
;     for (int i = 0; i < 16; ++i) { s0[i] *= f; s1[i] *= f; st.o0[i] *= alpha; st.o1[i] *= alpha; }
;     st.l *= alpha;
.Ldf_slow_a:
	s_nop 15
	v_lshlrev_b32_e32 v160, 2, v210
	v_xor_b32_e32 v160, 0x80, v160
	v_max_f32_e32 v161, v156, v156
	ds_bpermute_b32 v160, v160, v156
	s_waitcnt lgkmcnt(0)
	v_max_f32_e32 v160, v160, v160
	v_max_f32_e32 v160, v161, v160
	v_add_f32_e32 v160, v176, v160
	v_add_f32_e32 v161, v177, v157
	v_cmp_gt_f32_e32 vcc, v160, v161
	s_nop 1
	v_cndmask_b32_e32 v248, v177, v160, vcc
	v_sub_f32_e32 v160, v176, v248
	v_min_f32_e32 v160, 0x42f00000, v160
	v_sub_f32_e32 v161, v177, v248
	v_exp_f32_e32 v160, v160
	v_exp_f32_e32 v161, v161
	v_mov_b32_e32 v177, v248
	s_nop 0
	v_mul_f32_e32 v50, v50, v160
	v_mul_f32_e32 v34, v34, v160
	v_mul_f32_e32 v51, v51, v160
	v_mul_f32_e32 v35, v35, v160
	v_mul_f32_e32 v52, v52, v160
	v_mul_f32_e32 v36, v36, v160
	v_mul_f32_e32 v53, v53, v160
	v_mul_f32_e32 v37, v37, v160
	v_mul_f32_e32 v54, v54, v160
	v_mul_f32_e32 v38, v38, v160
	v_mul_f32_e32 v55, v55, v160
	v_mul_f32_e32 v39, v39, v160
	v_mul_f32_e32 v56, v56, v160
	v_mul_f32_e32 v40, v40, v160
	v_mul_f32_e32 v57, v57, v160
	v_mul_f32_e32 v41, v41, v160
	v_mul_f32_e32 v58, v58, v160
	v_mul_f32_e32 v42, v42, v160
	v_mul_f32_e32 v59, v59, v160
	v_mul_f32_e32 v43, v43, v160
	v_mul_f32_e32 v60, v60, v160
	v_mul_f32_e32 v44, v44, v160
	v_mul_f32_e32 v61, v61, v160
	v_mul_f32_e32 v45, v45, v160
	v_mul_f32_e32 v62, v62, v160
	v_mul_f32_e32 v46, v46, v160
	v_mul_f32_e32 v63, v63, v160
	v_mul_f32_e32 v47, v47, v160
	v_mul_f32_e32 v64, v64, v160
	v_mul_f32_e32 v48, v48, v160
	v_mul_f32_e32 v65, v65, v160
	v_mul_f32_e32 v49, v49, v160
	v_mul_f32_e32 v2, v2, v161
	v_mul_f32_e32 v3, v3, v161
	v_mul_f32_e32 v4, v4, v161
	v_mul_f32_e32 v5, v5, v161
	v_mul_f32_e32 v6, v6, v161
	v_mul_f32_e32 v7, v7, v161
	v_mul_f32_e32 v8, v8, v161
	v_mul_f32_e32 v9, v9, v161
	v_mul_f32_e32 v10, v10, v161
	v_mul_f32_e32 v11, v11, v161
	v_mul_f32_e32 v12, v12, v161
	v_mul_f32_e32 v13, v13, v161
	v_mul_f32_e32 v14, v14, v161
	v_mul_f32_e32 v15, v15, v161
	v_mul_f32_e32 v16, v16, v161
	v_mul_f32_e32 v17, v17, v161
	v_mul_f32_e32 v18, v18, v161
	v_mul_f32_e32 v19, v19, v161
	v_mul_f32_e32 v20, v20, v161
	v_mul_f32_e32 v21, v21, v161
	v_mul_f32_e32 v22, v22, v161
	v_mul_f32_e32 v23, v23, v161
	v_mul_f32_e32 v24, v24, v161
	v_mul_f32_e32 v25, v25, v161
	v_mul_f32_e32 v26, v26, v161
	v_mul_f32_e32 v27, v27, v161
	v_mul_f32_e32 v28, v28, v161
	v_mul_f32_e32 v29, v29, v161
	v_mul_f32_e32 v30, v30, v161
	v_mul_f32_e32 v31, v31, v161
	v_mul_f32_e32 v32, v32, v161
	v_mul_f32_e32 v33, v33, v161
	v_mul_f32_e32 v228, v228, v161
	s_branch .Ldf_back_a
.Ldf_slow_b:
	s_nop 15
	v_lshlrev_b32_e32 v160, 2, v210
	v_xor_b32_e32 v160, 0x80, v160
	v_max_f32_e32 v161, v247, v247
	ds_bpermute_b32 v160, v160, v247
	s_waitcnt lgkmcnt(0)
	v_max_f32_e32 v160, v160, v160
	v_max_f32_e32 v160, v161, v160
	v_add_f32_e32 v160, v176, v160
	v_add_f32_e32 v161, v177, v157
	v_cmp_gt_f32_e32 vcc, v160, v161
	s_nop 1
	v_cndmask_b32_e32 v248, v177, v160, vcc
	v_sub_f32_e32 v160, v176, v248
	v_min_f32_e32 v160, 0x42f00000, v160
	v_sub_f32_e32 v161, v177, v248
	v_exp_f32_e32 v160, v160
	v_exp_f32_e32 v161, v161
	v_mov_b32_e32 v177, v248
	s_nop 0
	v_mul_f32_e32 v82, v82, v160
	v_mul_f32_e32 v66, v66, v160
	v_mul_f32_e32 v83, v83, v160
	v_mul_f32_e32 v67, v67, v160
	v_mul_f32_e32 v84, v84, v160
	v_mul_f32_e32 v68, v68, v160
	v_mul_f32_e32 v85, v85, v160
	v_mul_f32_e32 v69, v69, v160
	v_mul_f32_e32 v86, v86, v160
	v_mul_f32_e32 v70, v70, v160
	v_mul_f32_e32 v87, v87, v160
	v_mul_f32_e32 v71, v71, v160
	v_mul_f32_e32 v88, v88, v160
	v_mul_f32_e32 v72, v72, v160
	v_mul_f32_e32 v89, v89, v160
	v_mul_f32_e32 v73, v73, v160
	v_mul_f32_e32 v90, v90, v160
	v_mul_f32_e32 v74, v74, v160
	v_mul_f32_e32 v91, v91, v160
	v_mul_f32_e32 v75, v75, v160
	v_mul_f32_e32 v92, v92, v160
	v_mul_f32_e32 v76, v76, v160
	v_mul_f32_e32 v93, v93, v160
	v_mul_f32_e32 v77, v77, v160
	v_mul_f32_e32 v94, v94, v160
	v_mul_f32_e32 v78, v78, v160
	v_mul_f32_e32 v95, v95, v160
	v_mul_f32_e32 v79, v79, v160
	v_mul_f32_e32 v96, v96, v160
	v_mul_f32_e32 v80, v80, v160
	v_mul_f32_e32 v97, v97, v160
	v_mul_f32_e32 v81, v81, v160
	v_mul_f32_e32 v2, v2, v161
	v_mul_f32_e32 v3, v3, v161
	v_mul_f32_e32 v4, v4, v161
	v_mul_f32_e32 v5, v5, v161
	v_mul_f32_e32 v6, v6, v161
	v_mul_f32_e32 v7, v7, v161
	v_mul_f32_e32 v8, v8, v161
	v_mul_f32_e32 v9, v9, v161
	v_mul_f32_e32 v10, v10, v161
	v_mul_f32_e32 v11, v11, v161
	v_mul_f32_e32 v12, v12, v161
	v_mul_f32_e32 v13, v13, v161
	v_mul_f32_e32 v14, v14, v161
	v_mul_f32_e32 v15, v15, v161
	v_mul_f32_e32 v16, v16, v161
	v_mul_f32_e32 v17, v17, v161
	v_mul_f32_e32 v18, v18, v161
	v_mul_f32_e32 v19, v19, v161
	v_mul_f32_e32 v20, v20, v161
	v_mul_f32_e32 v21, v21, v161
	v_mul_f32_e32 v22, v22, v161
	v_mul_f32_e32 v23, v23, v161
	v_mul_f32_e32 v24, v24, v161
	v_mul_f32_e32 v25, v25, v161
	v_mul_f32_e32 v26, v26, v161
	v_mul_f32_e32 v27, v27, v161
	v_mul_f32_e32 v28, v28, v161
	v_mul_f32_e32 v29, v29, v161
	v_mul_f32_e32 v30, v30, v161
	v_mul_f32_e32 v31, v31, v161
	v_mul_f32_e32 v32, v32, v161
	v_mul_f32_e32 v33, v33, v161
	v_mul_f32_e32 v228, v228, v161
	s_branch .Ldf_back_b
